# P1 projection phase: row rstd table of the XCD's 8 panels built once per phase in LDS; unit epilogues read 8 values with ds_read instead of 8 global loads + full vmcnt drain + 16 cross-lane reductions
# speedup vs baseline: 1.0030x; 1.0026x over previous
.LBB0_105:
	v_mov_b32_e32 v165, v27
	v_lshl_add_u64 v[58:59], s[86:87], 0, v[164:165]
	v_mov_b32_e32 v161, v27
	v_lshl_add_u64 v[84:85], s[86:87], 0, v[160:161]
	s_add_i32 m0, s17, 0x18000
	v_lshl_add_u64 v[58:59], v[58:59], 0, s[82:83]
	v_readlane_b32 s26, v251, 55
	v_mov_b32_e32 v167, v27
	s_waitcnt vmcnt(2)
	s_barrier
	global_load_lds_dwordx4 v[58:59], off
	v_lshl_add_u64 v[58:59], v[84:85], 0, s[82:83]
	s_add_i32 m0, s17, 0x1a000
	v_readlane_b32 s27, v251, 56
	s_add_i32 s22, s17, 0x8000
	v_mov_b32_e32 v163, v27
	global_load_lds_dwordx4 v[58:59], off
	v_lshl_add_u64 v[58:59], s[26:27], 0, v[166:167]
	s_mov_b32 m0, s22
	s_add_i32 s80, s17, 0xa000
	global_load_lds_dwordx4 v[58:59], off
	v_lshl_add_u64 v[58:59], s[26:27], 0, v[162:163]
	s_mov_b32 m0, s80
	s_and_b32 s1, s1, 3
	global_load_lds_dwordx4 v[58:59], off
	s_add_i32 m0, s17, 0x1c000
	v_lshl_add_u64 v[58:59], s[52:53], 0, v[164:165]
	global_load_lds_dwordx4 v[58:59], off
	v_lshl_add_u64 v[58:59], s[52:53], 0, v[160:161]
	s_add_i32 m0, s17, 0x1e000
	v_mul_lo_u32 v26, v26, s7
	global_load_lds_dwordx4 v[58:59], off
	v_bfe_u32 v59, v37, 4, 2
	v_and_b32_e32 v58, 15, v37
	v_lshlrev_b32_e32 v185, 4, v59
	v_lshlrev_b32_e32 v37, 2, v37
	v_lshl_or_b32 v184, s11, 6, v58
	v_lshl_or_b32 v58, v58, 6, v185
	s_lshl_b32 s11, s11, 13
	v_and_b32_e32 v37, 32, v37
	v_bitop3_b32 v84, v58, s11, v37 bitop3:0xde
	s_lshl_b32 s11, s1, 12
	v_bitop3_b32 v186, v58, s11, v37 bitop3:0xde
	s_cmpk_lt_u32 s0, 0x100
	v_lshrrev_b32_e32 v37, 1, v56
	v_mul_lo_u32 v58, v39, s7
	s_mov_b32 s11, 0x2c000
	s_cselect_b64 s[60:61], -1, 0
	v_cmp_eq_u32_e64 s[38:39], 0, v59
	s_lshl_b32 s26, s1, 1
	v_lshl_or_b32 v187, s1, 6, v185
	v_mad_u64_u32 v[58:59], s[0:1], v37, s11, v[58:59]
	v_and_b32_e32 v37, 1, v56
	v_lshl_or_b32 v37, v37, 6, v58
	v_lshl_add_u32 v176, v57, 1, v37
	v_lshrrev_b32_e32 v37, 1, v36
	v_mad_u64_u32 v[56:57], s[0:1], v37, s11, v[26:27]
	s_waitcnt vmcnt(6)
	v_and_b32_e32 v26, 1, v36
	v_readlane_b32 s0, v251, 36
	v_lshl_or_b32 v26, v26, 6, v56
	s_mov_b32 s94, s0
	v_readlane_b32 s0, v251, 34
	v_readlane_b32 s78, v251, 37
	s_mov_b32 s81, 0
	s_orn2_b32 s26, s26, 47
	v_mov_b32_e32 v177, v27
	v_lshl_add_u32 v178, v38, 1, v26
	v_mov_b32_e32 v179, v27
	v_add_u32_e32 v188, 0, v84
	v_readlane_b32 s31, v251, 35
	s_mov_b32 s30, s0
	s_mov_b64 s[76:77], s[86:87]
	v_readlane_b32 s79, v251, 38
	s_and_b32 s98, s94, -8
	s_lshl_b32 s98, s98, 14
	s_add_u32 s98, s57, s98
	s_addc_u32 s99, s15, 0
	v_lshlrev_b32_e32 v132, 6, v0
	v_add_u32_e32 v133, 0x8000, v132
	v_add_u32_e32 v134, 0x10000, v132
	v_add_u32_e32 v135, 0x18000, v132
	global_load_dwordx4 v[100:103], v132, s[98:99]
	global_load_dwordx4 v[104:107], v132, s[98:99] offset:16
	global_load_dwordx4 v[108:111], v132, s[98:99] offset:32
	global_load_dwordx4 v[112:115], v132, s[98:99] offset:48
	global_load_dwordx4 v[116:119], v133, s[98:99]
	global_load_dwordx4 v[120:123], v133, s[98:99] offset:16
	global_load_dwordx4 v[124:127], v133, s[98:99] offset:32
	global_load_dwordx4 v[128:131], v133, s[98:99] offset:48
	global_load_dwordx4 v[190:193], v134, s[98:99]
	global_load_dwordx4 v[194:197], v134, s[98:99] offset:16
	global_load_dwordx4 v[198:201], v134, s[98:99] offset:32
	global_load_dwordx4 v[202:205], v134, s[98:99] offset:48
	global_load_dwordx4 v[206:209], v135, s[98:99]
	global_load_dwordx4 v[210:213], v135, s[98:99] offset:16
	global_load_dwordx4 v[214:217], v135, s[98:99] offset:32
	global_load_dwordx4 v[218:221], v135, s[98:99] offset:48
	v_lshlrev_b32_e32 v140, 2, v0
	v_add_u32_e32 v140, 0x20000, v140
	s_waitcnt vmcnt(0)
	v_add_f32_e32 v101, v101, v100
	v_add_f32_e32 v102, v102, v103
	v_add_f32_e32 v100, v101, v102
	v_add_f32_e32 v105, v105, v104
	v_add_f32_e32 v106, v106, v107
	v_add_f32_e32 v104, v105, v106
	v_add_f32_e32 v109, v109, v108
	v_add_f32_e32 v110, v110, v111
	v_add_f32_e32 v108, v109, v110
	v_add_f32_e32 v113, v113, v112
	v_add_f32_e32 v114, v114, v115
	v_add_f32_e32 v112, v113, v114
	v_add_f32_e32 v100, v100, v104
	v_add_f32_e32 v108, v108, v112
	v_add_f32_e32 v136, v100, v108
	v_add_f32_e32 v117, v117, v116
	v_add_f32_e32 v118, v118, v119
	v_add_f32_e32 v116, v117, v118
	v_add_f32_e32 v121, v121, v120
	v_add_f32_e32 v122, v122, v123
	v_add_f32_e32 v120, v121, v122
	v_add_f32_e32 v125, v125, v124
	v_add_f32_e32 v126, v126, v127
	v_add_f32_e32 v124, v125, v126
	v_add_f32_e32 v129, v129, v128
	v_add_f32_e32 v130, v130, v131
	v_add_f32_e32 v128, v129, v130
	v_add_f32_e32 v116, v116, v120
	v_add_f32_e32 v124, v124, v128
	v_add_f32_e32 v137, v116, v124
	v_add_f32_e32 v191, v191, v190
	v_add_f32_e32 v192, v192, v193
	v_add_f32_e32 v190, v191, v192
	v_add_f32_e32 v195, v195, v194
	v_add_f32_e32 v196, v196, v197
	v_add_f32_e32 v194, v195, v196
	v_add_f32_e32 v199, v199, v198
	v_add_f32_e32 v200, v200, v201
	v_add_f32_e32 v198, v199, v200
	v_add_f32_e32 v203, v203, v202
	v_add_f32_e32 v204, v204, v205
	v_add_f32_e32 v202, v203, v204
	v_add_f32_e32 v190, v190, v194
	v_add_f32_e32 v198, v198, v202
	v_add_f32_e32 v138, v190, v198
	v_add_f32_e32 v207, v207, v206
	v_add_f32_e32 v208, v208, v209
	v_add_f32_e32 v206, v207, v208
	v_add_f32_e32 v211, v211, v210
	v_add_f32_e32 v212, v212, v213
	v_add_f32_e32 v210, v211, v212
	v_add_f32_e32 v215, v215, v214
	v_add_f32_e32 v216, v216, v217
	v_add_f32_e32 v214, v215, v216
	v_add_f32_e32 v219, v219, v218
	v_add_f32_e32 v220, v220, v221
	v_add_f32_e32 v218, v219, v220
	v_add_f32_e32 v206, v206, v210
	v_add_f32_e32 v214, v214, v218
	v_add_f32_e32 v139, v206, v214
	v_fmamk_f32 v136, v136, 0x3a800000, v222
	v_fmamk_f32 v137, v137, 0x3a800000, v222
	v_fmamk_f32 v138, v138, 0x3a800000, v222
	v_fmamk_f32 v139, v139, 0x3a800000, v222
	v_rsq_f32_e32 v136, v136
	v_rsq_f32_e32 v137, v137
	v_rsq_f32_e32 v138, v138
	v_rsq_f32_e32 v139, v139
	s_nop 0
	ds_write_b32 v140, v136
	ds_write_b32 v140, v137 offset:2048
	ds_write_b32 v140, v138 offset:4096
	ds_write_b32 v140, v139 offset:6144
	s_waitcnt lgkmcnt(0)
	s_barrier
	s_branch .LBB0_108

.LBB0_114:
	s_ashr_i32 s95, s94, 31
	s_and_b32 s98, s94, 7
	s_lshl_b32 s98, s98, 10
	v_mov_b32_e32 v181, v184
	s_lshl_b64 s[0:1], s[94:95], 14
	s_add_u32 s0, s57, s0
	v_lshlrev_b32_e32 v26, 6, v181
	s_addc_u32 s1, s15, s1
	v_or_b32_e32 v36, v26, v185
	v_mov_b32_e32 v37, v27
	v_lshl_add_u64 v[38:39], s[0:1], 0, v[36:37]
	v_add_co_u32_e32 v36, vcc, s6, v38
	v_and_b32_e32 v182, 64, v224
	s_nop 0
	v_addc_co_u32_e32 v37, vcc, 0, v39, vcc
	s_nop 0
	v_xor_b32_e32 v180, 16, v224
	v_add_u32_e32 v194, 64, v182
	v_cmp_lt_i32_e32 vcc, v180, v194
	s_cmp_eq_u32 s31, 3
	s_cselect_b64 s[88:89], -1, 0
	v_cndmask_b32_e32 v180, v224, v180, vcc
	v_lshlrev_b32_e32 v189, 2, v180
	s_cmp_lg_u32 s31, 3
	v_xor_b32_e32 v183, 32, v224
	v_cmp_lt_i32_e32 vcc, v183, v194
	s_nop 1
	v_cndmask_b32_e32 v183, v224, v183, vcc
	v_lshlrev_b32_e32 v190, 2, v183
	v_lshl_add_u32 v200, v181, 2, s98
	v_add_u32_e32 v200, 0x20000, v200
	ds_read_b32 v242, v200
	ds_read_b32 v243, v200 offset:64
	ds_read_b32 v244, v200 offset:128
	ds_read_b32 v245, v200 offset:192
	ds_read_b32 v246, v200 offset:512
	ds_read_b32 v247, v200 offset:576
	ds_read_b32 v248, v200 offset:640
	ds_read_b32 v249, v200 offset:704
	s_waitcnt lgkmcnt(0)
	v_mov_b32_e32 v180, v242
	v_pk_mul_f32 v[150:151], v[150:151], v[180:181] op_sel_hi:[1,0]
	v_pk_mul_f32 v[148:149], v[148:149], v[180:181] op_sel_hi:[1,0]
	v_pk_mul_f32 v[154:155], v[154:155], v[180:181] op_sel_hi:[1,0]
	v_pk_mul_f32 v[182:183], v[152:153], v[180:181] op_sel_hi:[1,0]
	s_cbranch_scc1 .LBB0_116
	v_pk_mul_f32 v[152:153], v[150:151], v[150:151]
	v_pk_mul_f32 v[192:193], v[148:149], v[148:149]
	v_mov_b64_e32 v[194:195], s[42:43]
	v_pk_mul_f32 v[196:197], v[154:155], v[154:155]
	v_pk_mul_f32 v[198:199], v[182:183], v[182:183]
	v_pk_fma_f32 v[192:193], v[192:193], s[18:19], v[194:195] op_sel_hi:[1,0,0] neg_lo:[1,0,0] neg_hi:[1,0,0]
	v_pk_fma_f32 v[198:199], v[198:199], s[18:19], v[194:195] op_sel_hi:[1,0,0] neg_lo:[1,0,0] neg_hi:[1,0,0]
	v_pk_fma_f32 v[152:153], v[152:153], s[18:19], v[194:195] op_sel_hi:[1,0,0] neg_lo:[1,0,0] neg_hi:[1,0,0]
	v_pk_fma_f32 v[194:195], v[196:197], s[18:19], v[194:195] op_sel_hi:[1,0,0] neg_lo:[1,0,0] neg_hi:[1,0,0]
	v_pk_mul_f32 v[192:193], v[148:149], v[192:193]
	v_pk_mul_f32 v[198:199], v[182:183], v[198:199]
	v_pk_mul_f32 v[152:153], v[150:151], v[152:153]
	v_pk_mul_f32 v[194:195], v[154:155], v[194:195]
	v_exp_f32_e32 v192, v192
	v_exp_f32_e32 v193, v193
	v_exp_f32_e32 v198, v198
	v_exp_f32_e32 v199, v199
	v_exp_f32_e32 v152, v152
	v_exp_f32_e32 v153, v153
	v_exp_f32_e32 v194, v194
	v_exp_f32_e32 v195, v195
	v_pk_add_f32 v[192:193], v[192:193], 1.0 op_sel_hi:[1,0]
	v_pk_add_f32 v[198:199], v[198:199], 1.0 op_sel_hi:[1,0]
	v_pk_add_f32 v[152:153], v[152:153], 1.0 op_sel_hi:[1,0]
	v_pk_add_f32 v[194:195], v[194:195], 1.0 op_sel_hi:[1,0]
	v_rcp_f32_e32 v192, v192
	v_rcp_f32_e32 v193, v193
	v_rcp_f32_e32 v198, v198
	v_rcp_f32_e32 v199, v199
	v_rcp_f32_e32 v152, v152
	v_rcp_f32_e32 v153, v153
	v_rcp_f32_e32 v194, v194
	v_rcp_f32_e32 v195, v195
	v_pk_mul_f32 v[148:149], v[148:149], v[192:193]
	v_pk_mul_f32 v[150:151], v[150:151], v[152:153]
	v_pk_mul_f32 v[182:183], v[182:183], v[198:199]
	v_pk_mul_f32 v[154:155], v[154:155], v[194:195]
